# v30 + one 4-byte pad at the KIND2 loop head so the net size change since v29 is 0 mod 8 bytes (code-placement check)
# speedup vs baseline: 1.0056x; 1.0056x over previous
.LBB0_672:
	s_nop 0
	s_add_i32 s30, s31, 1
	s_cmp_lt_u32 s30, s20
	s_cselect_b64 s[22:23], -1, 0
	s_cmp_ge_u32 s30, s20
	s_cbranch_scc1 .LBB0_674
	s_add_i32 s40, s21, s31
	s_cmp_lt_u32 s31, 3
	s_cselect_b32 s40, s30, s40
	s_lshl_b32 s40, s40, 6
	s_add_i32 s41, s40, s27
	v_add_u32_e32 v2, s41, v175
	v_ashrrev_i32_e32 v3, 31, v2
	v_lshlrev_b64 v[2:3], v170, v[2:3]
	v_lshl_add_u64 v[2:3], v[172:173], 0, v[2:3]
	global_load_dwordx4 v[144:147], v[2:3], off
	v_add_u32_e32 v2, s41, v179
	v_ashrrev_i32_e32 v3, 31, v2
	v_lshlrev_b64 v[2:3], v174, v[2:3]
	v_lshl_add_u64 v[2:3], v[176:177], 0, v[2:3]
	global_load_dwordx4 v[148:151], v[2:3], off
	v_add_u32_e32 v2, s41, v183
	v_ashrrev_i32_e32 v3, 31, v2
	v_lshlrev_b64 v[2:3], v178, v[2:3]
	s_ashr_i32 s41, s40, 31
	v_lshl_add_u64 v[2:3], v[180:181], 0, v[2:3]
	s_lshl_b64 s[40:41], s[40:41], 1
	global_load_dwordx4 v[152:155], v[2:3], off
	v_lshl_add_u64 v[2:3], v[166:167], 0, s[40:41]
	v_lshl_add_u64 v[4:5], v[168:169], 0, s[40:41]
	global_load_dwordx4 v[156:159], v[2:3], off
	global_load_dwordx4 v[160:163], v[4:5], off
